# attention: counted lgkmcnt waits in PV + static s_setprio 1 for waves 4-7
# speedup vs baseline: 1.0171x; 1.0171x over previous
.LBB0_2051:
	s_or_b64 exec, exec, s[4:5]
	s_waitcnt lgkmcnt(0)
	s_barrier
	v_readlane_b32 s100, v255, 6
	s_nop 3
	s_cmp_lt_u32 s100, 4
	s_cbranch_scc1 .Laprio_skip
	s_setprio 1
.Laprio_skip:
.LBB0_2052:
	s_cmp_gt_i32 s60, 28
	s_cselect_b64 s[4:5], -1, 0
	s_cmp_lt_i32 s61, 29
	s_cselect_b64 s[6:7], -1, 0
	s_or_b64 s[4:5], s[4:5], s[6:7]
	s_and_b64 vcc, exec, s[4:5]
	s_cbranch_vccnz .LBB0_2131
	s_waitcnt vmcnt(1)
	v_lshrrev_b32_e32 v11, 3, v0
	v_lshrrev_b32_e32 v8, 4, v0
	v_and_b32_e32 v11, 8, v11
	v_lshlrev_b32_e32 v9, 3, v0
	v_and_or_b32 v12, v8, 16, v11
	v_and_b32_e32 v10, 0x78, v9
	v_lshrrev_b32_e32 v13, 5, v0
	v_lshrrev_b32_e32 v12, 1, v12
	s_waitcnt vmcnt(0)
	v_bfe_u32 v14, v9, 5, 2
	v_bfe_u32 v15, v0, 4, 2
	v_or_b32_e32 v12, v12, v14
	v_and_or_b32 v13, v13, 4, v15
	v_lshlrev_b32_e32 v15, 1, v10
	v_lshlrev_b32_e32 v12, 9, v12
	v_lshlrev_b32_e32 v13, 6, v13
	v_and_b32_e32 v16, 48, v15
	v_or3_b32 v17, v12, v13, v16
	v_or_b32_e32 v12, 32, v8
	v_and_or_b32 v11, v12, 48, v11
	v_lshrrev_b32_e32 v11, 1, v11
	v_or_b32_e32 v11, v11, v14
	v_lshlrev_b32_e32 v11, 9, v11
	v_or3_b32 v11, v11, v13, v16
	v_lshlrev_b32_e32 v13, 4, v0
	v_lshlrev_b32_e32 v16, 1, v0
	v_bfe_u32 v3, v0, 5, 1
	v_and_b32_e32 v14, 0xc0, v13
	v_and_b32_e32 v16, 32, v16
	v_and_b32_e32 v9, 0x118, v9
	v_and_b32_e32 v2, 31, v0
	v_or3_b32 v9, v16, v14, v9
	v_lshlrev_b32_e32 v14, 8, v8
	v_lshlrev_b32_e32 v12, 8, v12
	v_and_b32_e32 v16, 0x70, v0
	v_lshlrev_b32_e32 v21, 4, v3
	s_lshl_b32 s3, s2, 7
	v_or_b32_e32 v8, v14, v10
	v_or_b32_e32 v10, v12, v10
	v_bitop3_b32 v19, v15, v14, v16 bitop3:0xde
	v_bitop3_b32 v15, v15, v12, v16 bitop3:0xde
	v_lshlrev_b32_e32 v12, 8, v2
	v_and_b32_e32 v13, 0x70, v13
	v_or_b32_e32 v14, 32, v21
	s_and_b32 s3, s3, 0x380
	s_lshr_b32 s4, s2, 3
	v_bitop3_b32 v23, v14, v12, v13 bitop3:0xde
	v_or_b32_e32 v14, 64, v21
	s_add_i32 s3, s3, s4
	v_bitop3_b32 v24, v14, v12, v13 bitop3:0xde
	v_or_b32_e32 v14, 0x60, v21
	v_bitop3_b32 v25, v14, v12, v13 bitop3:0xde
	v_or_b32_e32 v14, 0x80, v21
	s_cmpk_lg_i32 s56, 0x100
	v_lshrrev_b32_e32 v4, 1, v0
	v_bitop3_b32 v26, v14, v12, v13 bitop3:0xde
	v_or_b32_e32 v14, 0xa0, v21
	s_cselect_b64 s[26:27], -1, 0
	s_add_i32 s6, 0, 0x10000
	v_and_b32_e32 v5, 0x1c0, v0
	v_and_b32_e32 v7, 0xe0, v4
	v_bitop3_b32 v27, v14, v12, v13 bitop3:0xde
	v_or_b32_e32 v14, 0xc0, v21
	s_cmp_lg_u32 0, -1
	v_and_b32_e32 v1, 63, v0
	v_or_b32_e32 v4, v7, v2
	v_lshlrev_b32_e32 v6, 3, v3
	v_bitop3_b32 v28, v14, v12, v13 bitop3:0xde
	v_or_b32_e32 v14, 0xe0, v21
	v_lshlrev_b32_e32 v180, 13, v3
	v_lshl_add_u32 v3, v5, 2, s6
	s_cselect_b32 s6, 0, 0
	v_mul_u32_u24_e32 v4, 0x600, v4
	v_mov_b32_e32 v179, 0
	v_bitop3_b32 v22, v21, v12, v13 bitop3:0xde
	v_bitop3_b32 v13, v14, v12, v13 bitop3:0xde
	v_or_b32_e32 v12, 0x4000, v8
	v_or_b32_e32 v14, 0x6000, v8
	v_or_b32_e32 v16, 0x8000, v8
	v_or_b32_e32 v18, 0xa000, v8
	v_cmp_gt_u32_e64 s[4:5], 32, v1
	v_lshlrev_b32_e32 v20, 10, v7
	v_add_u32_e32 v1, s6, v9
	v_lshl_add_u32 v196, v2, 2, v3
	s_addk_i32 s6, 0x4000
	v_add_u32_e32 v198, v3, v21
	v_lshlrev_b32_e32 v3, 1, v8
	s_movk_i32 s29, 0x4000
	s_mov_b32 s36, 0x8000
	v_mov_b32_e32 v181, v179
	s_mov_b32 s8, 0
	v_add_u32_e32 v197, s6, v9
	v_or_b32_e32 v182, 0x24000, v3
	v_mov_b32_e32 v183, v179
	v_or_b32_e32 v184, 0x20000, v3
	v_mov_b32_e32 v185, v179
	v_or_b32_e32 v186, 0x18000, v3
	v_mov_b32_e32 v187, v179
	v_or_b32_e32 v188, 0x1c000, v3
	v_mov_b32_e32 v189, v179
	s_mov_b32 s37, 0x42b504f3
	s_mov_b32 s28, 0x3e0293ee
	s_mov_b32 s38, 0x27800000
	s_mov_b32 s39, 0x26700000
	v_lshlrev_b32_e32 v178, 1, v20
	v_lshlrev_b32_e32 v190, 1, v2
	s_movk_i32 s41, 0x7fff
	s_movk_i32 s42, 0x1000
	s_movk_i32 s43, 0x5000
	s_mov_b32 s45, 0x9000
	s_mov_b32 s46, 0xc000
	s_mov_b32 s47, 0xd000
	v_lshlrev_b32_e32 v192, 1, v4
	v_lshlrev_b32_e32 v194, 1, v6
	v_lshlrev_b32_e32 v199, 1, v8
	v_lshlrev_b32_e32 v200, 1, v10
	v_add_u32_e32 v201, 0, v17
	v_add_u32_e32 v202, 0, v11
	v_add_u32_e32 v203, 0, v19
	v_add_u32_e32 v204, 0, v15
	v_add_u32_e32 v205, 0, v22
	v_add_u32_e32 v206, 0, v23
	v_add_u32_e32 v207, 0, v24
	v_add_u32_e32 v208, 0, v25
	v_add_u32_e32 v209, 0, v26
	v_add_u32_e32 v210, 0, v27
	v_add_u32_e32 v211, 0, v28
	v_add_u32_e32 v212, 0, v13
	v_mov_b32_e32 v213, 0xf149f2ca
	v_lshlrev_b32_e32 v214, 1, v12
	v_lshlrev_b32_e32 v215, 1, v14
	v_lshlrev_b32_e32 v216, 1, v16
	v_lshlrev_b32_e32 v217, 1, v18
	s_mov_b32 s49, 0
	s_branch .LBB0_2056

.LBB0_2063:
	ds_read_b128 v[66:69], v205 offset:49152
	ds_read_b128 v[70:73], v205 offset:57344
	ds_read_b128 v[224:227], v206 offset:49152
	ds_read_b128 v[228:231], v206 offset:57344
	v_add_f32_e32 v162, 0, v177
	v_add_f32_e32 v162, v223, v162
	s_waitcnt lgkmcnt(3)
	v_mfma_f32_32x32x16_bf16 v[82:97], v[66:69], v[126:129], 0
	v_add_f32_e32 v162, v163, v162
	v_add_f32_e32 v162, v220, v162
	v_add_f32_e32 v162, v164, v162
	v_add_f32_e32 v162, v176, v162
	v_add_f32_e32 v162, v165, v162
	v_add_f32_e32 v162, v175, v162
	v_add_f32_e32 v162, v172, v162
	s_waitcnt lgkmcnt(2)
	v_mfma_f32_32x32x16_bf16 v[66:81], v[70:73], v[126:129], 0
	v_add_f32_e32 v162, v174, v162
	v_add_f32_e32 v162, v171, v162
	v_add_f32_e32 v162, v173, v162
	v_exp_f32_e32 v156, v156
	v_add_f32_e32 v162, v168, v162
	v_exp_f32_e32 v157, v157
	v_add_f32_e32 v162, v170, v162
	s_waitcnt lgkmcnt(1)
	v_mfma_f32_32x32x16_bf16 v[82:97], v[224:227], v[122:125], v[82:97]
	v_exp_f32_e32 v154, v154
	v_add_f32_e32 v162, v167, v162
	v_exp_f32_e32 v155, v155
	v_add_f32_e32 v162, v169, v162
	v_exp_f32_e32 v150, v150
	v_add_f32_e32 v162, v156, v162
	v_exp_f32_e32 v151, v151
	s_waitcnt lgkmcnt(0)
	v_mfma_f32_32x32x16_bf16 v[66:81], v[228:231], v[122:125], v[66:81]
	ds_read_b128 v[224:227], v207 offset:49152
	ds_read_b128 v[228:231], v207 offset:57344
	v_add_f32_e32 v162, v157, v162
	v_exp_f32_e32 v148, v148
	v_add_f32_e32 v162, v154, v162
	v_exp_f32_e32 v149, v149
	v_add_f32_e32 v162, v155, v162
	v_exp_f32_e32 v146, v146
	s_waitcnt lgkmcnt(1)
	v_mfma_f32_32x32x16_bf16 v[82:97], v[224:227], v[118:121], v[82:97]
	v_add_f32_e32 v162, v150, v162
	v_exp_f32_e32 v147, v147
	v_add_f32_e32 v162, v151, v162
	v_exp_f32_e32 v160, v160
	v_add_f32_e32 v162, v148, v162
	v_exp_f32_e32 v161, v161
	v_add_f32_e32 v162, v149, v162
	s_waitcnt lgkmcnt(0)
	v_mfma_f32_32x32x16_bf16 v[66:81], v[228:231], v[118:121], v[66:81]
	ds_read_b128 v[224:227], v208 offset:49152
	ds_read_b128 v[228:231], v208 offset:57344
	v_exp_f32_e32 v158, v158
	v_add_f32_e32 v162, v146, v162
	v_exp_f32_e32 v159, v159
	v_add_f32_e32 v162, v147, v162
	v_exp_f32_e32 v152, v152
	v_add_f32_e32 v162, v160, v162
	s_waitcnt lgkmcnt(1)
	v_mfma_f32_32x32x16_bf16 v[82:97], v[224:227], v[114:117], v[82:97]
	v_exp_f32_e32 v153, v153
	v_add_f32_e32 v162, v161, v162
	v_add_f32_e32 v162, v158, v162
	v_add_f32_e32 v162, v159, v162
	v_add_f32_e32 v162, v152, v162
	v_add_f32_e32 v195, v153, v162
	v_mov_b32_e32 v218, v195
	s_waitcnt lgkmcnt(0)
	v_mfma_f32_32x32x16_bf16 v[66:81], v[228:231], v[114:117], v[66:81]
	ds_read_b128 v[224:227], v209 offset:49152
	ds_read_b128 v[228:231], v209 offset:57344
	v_permlane32_swap_b32_e32 v195, v218
	s_waitcnt lgkmcnt(1)
	v_mfma_f32_32x32x16_bf16 v[82:97], v[224:227], v[110:113], v[82:97]
	s_waitcnt lgkmcnt(0)
	v_mfma_f32_32x32x16_bf16 v[66:81], v[228:231], v[110:113], v[66:81]
	ds_read_b128 v[224:227], v210 offset:49152
	ds_read_b128 v[228:231], v210 offset:57344
	s_waitcnt lgkmcnt(1)
	v_mfma_f32_32x32x16_bf16 v[82:97], v[224:227], v[106:109], v[82:97]
	s_waitcnt lgkmcnt(0)
	v_mfma_f32_32x32x16_bf16 v[66:81], v[228:231], v[106:109], v[66:81]
	ds_read_b128 v[224:227], v211 offset:49152
	ds_read_b128 v[228:231], v211 offset:57344
	s_waitcnt lgkmcnt(1)
	v_mfma_f32_32x32x16_bf16 v[82:97], v[224:227], v[102:105], v[82:97]
	s_waitcnt lgkmcnt(0)
	v_mfma_f32_32x32x16_bf16 v[66:81], v[228:231], v[102:105], v[66:81]
	ds_read_b128 v[224:227], v212 offset:49152
	ds_read_b128 v[228:231], v212 offset:57344
	v_cvt_pk_bf16_f32 v162, v177, v223
	v_cvt_pk_bf16_f32 v163, v163, v220
	v_cvt_pk_bf16_f32 v164, v164, v176
	v_cvt_pk_bf16_f32 v165, v165, v175
	v_cvt_pk_bf16_f32 v172, v172, v174
	v_cvt_pk_bf16_f32 v173, v171, v173
	s_waitcnt lgkmcnt(1)
	v_mfma_f32_32x32x16_bf16 v[82:97], v[224:227], v[98:101], v[82:97]
	v_permlane32_swap_b32_e32 v162, v164
	v_cvt_pk_bf16_f32 v174, v168, v170
	v_cvt_pk_bf16_f32 v175, v167, v169
	v_cvt_pk_bf16_f32 v168, v156, v157
	v_cvt_pk_bf16_f32 v169, v154, v155
	v_cvt_pk_bf16_f32 v170, v150, v151
	s_waitcnt lgkmcnt(0)
	v_mfma_f32_32x32x16_bf16 v[66:81], v[228:231], v[98:101], v[66:81]
	v_cvt_pk_bf16_f32 v171, v148, v149
	v_cvt_pk_bf16_f32 v220, v146, v147
	v_cvt_pk_bf16_f32 v221, v160, v161
	v_cvt_pk_bf16_f32 v222, v158, v159
	v_cvt_pk_bf16_f32 v223, v152, v153
	v_permlane32_swap_b32_e32 v163, v165
	v_permlane32_swap_b32_e32 v172, v174
	v_permlane32_swap_b32_e32 v173, v175
	v_permlane32_swap_b32_e32 v168, v170
	v_permlane32_swap_b32_e32 v169, v171
	v_permlane32_swap_b32_e32 v220, v222
	v_permlane32_swap_b32_e32 v221, v223
	v_lshl_add_u64 v[154:155], s[10:11], 0, v[186:187]
	v_add_co_u32_e32 v146, vcc, s38, v154
	v_lshl_add_u64 v[156:157], s[10:11], 0, v[188:189]
	s_nop 0
	v_addc_co_u32_e32 v147, vcc, 0, v155, vcc
	v_add_co_u32_e32 v150, vcc, s38, v156
	s_nop 1
	v_addc_co_u32_e32 v151, vcc, 0, v157, vcc
	v_add_co_u32_e32 v154, vcc, s39, v154
	global_load_dwordx4 v[146:149], v[146:147], off
	s_nop 0
	global_load_dwordx4 v[150:153], v[150:151], off
	v_addc_co_u32_e32 v155, vcc, 0, v155, vcc
	v_add_co_u32_e32 v158, vcc, s39, v156
	s_nop 1
	v_addc_co_u32_e32 v159, vcc, 0, v157, vcc
	global_load_dwordx4 v[154:157], v[154:155], off
	s_nop 0
	global_load_dwordx4 v[158:161], v[158:159], off
	s_waitcnt vmcnt(4)
	ds_write_b128 v203, v[138:141] offset:32768
	ds_write_b128 v204, v[142:145] offset:32768
	ds_read_b64_tr_b16 v[224:225], v1 offset:0
	ds_read_b64_tr_b16 v[226:227], v1 offset:0x800
	ds_read_b64_tr_b16 v[228:229], v1 offset:0x1000
	ds_read_b64_tr_b16 v[230:231], v1 offset:0x1800
	ds_read_b64_tr_b16 v[232:233], v1 offset:0x2000
	ds_read_b64_tr_b16 v[234:235], v1 offset:0x2800
	ds_read_b64_tr_b16 v[236:237], v1 offset:0x3000
	ds_read_b64_tr_b16 v[238:239], v1 offset:0x3800
	s_nop 0
	s_waitcnt lgkmcnt(6)
	v_mfma_f32_32x32x16_bf16 v[2:17], v[162:165], v[224:227], v[2:17]
	ds_read_b64_tr_b16 v[224:225], v1 offset:0x200
	ds_read_b64_tr_b16 v[226:227], v1 offset:0xa00
	s_waitcnt lgkmcnt(6)
	v_mfma_f32_32x32x16_bf16 v[2:17], v[172:175], v[228:231], v[2:17]
	ds_read_b64_tr_b16 v[228:229], v1 offset:0x1200
	ds_read_b64_tr_b16 v[230:231], v1 offset:0x1a00
	s_waitcnt lgkmcnt(6)
	v_mfma_f32_32x32x16_bf16 v[2:17], v[168:171], v[232:235], v[2:17]
	ds_read_b64_tr_b16 v[232:233], v1 offset:0x2200
	ds_read_b64_tr_b16 v[234:235], v1 offset:0x2a00
	ds_read_b64_tr_b16 v[240:241], v1 offset:0x3200
	ds_read_b64_tr_b16 v[242:243], v1 offset:0x3a00
	s_waitcnt lgkmcnt(8)
	v_mfma_f32_32x32x16_bf16 v[2:17], v[220:223], v[236:239], v[2:17]
	s_waitcnt lgkmcnt(6)
	v_mfma_f32_32x32x16_bf16 v[50:65], v[162:165], v[224:227], v[50:65]
	ds_read_b64_tr_b16 v[224:225], v1 offset:0x400
	ds_read_b64_tr_b16 v[226:227], v1 offset:0xc00
	s_waitcnt lgkmcnt(6)
	v_mfma_f32_32x32x16_bf16 v[50:65], v[172:175], v[228:231], v[50:65]
	ds_read_b64_tr_b16 v[228:229], v1 offset:0x1400
	ds_read_b64_tr_b16 v[230:231], v1 offset:0x1c00
	s_waitcnt lgkmcnt(6)
	v_mfma_f32_32x32x16_bf16 v[50:65], v[168:171], v[232:235], v[50:65]
	ds_read_b64_tr_b16 v[232:233], v1 offset:0x2400
	ds_read_b64_tr_b16 v[234:235], v1 offset:0x2c00
	ds_read_b64_tr_b16 v[236:237], v1 offset:0x3400
	ds_read_b64_tr_b16 v[238:239], v1 offset:0x3c00
	s_waitcnt lgkmcnt(8)
	v_mfma_f32_32x32x16_bf16 v[50:65], v[220:223], v[240:243], v[50:65]
	s_waitcnt lgkmcnt(6)
	v_mfma_f32_32x32x16_bf16 v[34:49], v[162:165], v[224:227], v[34:49]
	ds_read_b64_tr_b16 v[224:225], v1 offset:0x600
	ds_read_b64_tr_b16 v[226:227], v1 offset:0xe00
	s_waitcnt lgkmcnt(6)
	v_mfma_f32_32x32x16_bf16 v[34:49], v[172:175], v[228:231], v[34:49]
	ds_read_b64_tr_b16 v[228:229], v1 offset:0x1600
	ds_read_b64_tr_b16 v[230:231], v1 offset:0x1e00
	s_waitcnt lgkmcnt(6)
	v_mfma_f32_32x32x16_bf16 v[34:49], v[168:171], v[232:235], v[34:49]
	ds_read_b64_tr_b16 v[232:233], v1 offset:0x2600
	ds_read_b64_tr_b16 v[234:235], v1 offset:0x2e00
	ds_read_b64_tr_b16 v[240:241], v1 offset:0x3600
	ds_read_b64_tr_b16 v[242:243], v1 offset:0x3e00
	s_waitcnt lgkmcnt(8)
	v_mfma_f32_32x32x16_bf16 v[34:49], v[220:223], v[236:239], v[34:49]
	s_waitcnt lgkmcnt(6)
	v_mfma_f32_32x32x16_bf16 v[18:33], v[162:165], v[224:227], v[18:33]
	v_max_f32_e32 v167, v83, v83
	v_max_f32_e32 v176, v82, v82
	v_max_f32_e32 v167, v176, v167
	v_max3_f32 v167, v167, v84, v85
	v_max3_f32 v167, v167, v86, v87
	v_max3_f32 v162, v167, v88, v89
	v_max3_f32 v162, v162, v90, v91
	v_max3_f32 v162, v162, v92, v93
	s_waitcnt lgkmcnt(4)
	v_mfma_f32_32x32x16_bf16 v[18:33], v[172:175], v[228:231], v[18:33]
	v_max3_f32 v162, v162, v94, v95
	v_max3_f32 v162, v162, v96, v97
	v_max3_f32 v162, v162, v66, v67
	v_max3_f32 v162, v162, v68, v69
	v_max3_f32 v162, v162, v70, v71
	v_max3_f32 v162, v162, v72, v73
	v_max3_f32 v162, v162, v74, v75
	v_max3_f32 v162, v162, v76, v77
	s_waitcnt lgkmcnt(2)
	v_mfma_f32_32x32x16_bf16 v[18:33], v[168:171], v[232:235], v[18:33]
	v_max3_f32 v162, v162, v78, v79
	v_max3_f32 v162, v162, v80, v81
	v_mov_b32_e32 v163, v162
	s_nop 1
	v_permlane32_swap_b32_e32 v162, v163
	v_max_f32_e32 v163, v163, v163
	v_max_f32_e32 v162, v162, v162
	v_max_f32_e32 v162, v162, v163
	v_max_f32_e32 v164, v166, v166
	v_sub_f32_e32 v163, v162, v166
	v_max_f32_e32 v162, v164, v162
	s_waitcnt lgkmcnt(0)
	v_mfma_f32_32x32x16_bf16 v[18:33], v[220:223], v[240:243], v[18:33]
	v_sub_f32_e32 v164, v166, v162
	v_mul_f32_e32 v164, 0x3e0293ee, v164
	v_exp_f32_e32 v164, v164
	v_cmp_ge_f32_e32 vcc, s37, v163
	s_cmp_eq_u64 vcc, exec
	s_cselect_b64 s[6:7], -1, 0
	s_barrier
	s_waitcnt vmcnt(4)
	v_cndmask_b32_e64 v219, v164, 1.0, s[6:7]
	v_cmp_gt_f32_e32 vcc, 1.0, v219
	ds_write_b128 v201, v[130:133]
	ds_write_b128 v202, v[134:137]
	s_cbranch_vccz .LBB0_2067
	s_and_saveexec_b64 s[12:13], s[4:5]
	ds_write_b32 v196, v219 offset:128
	s_or_b64 exec, exec, s[12:13]
	s_waitcnt lgkmcnt(0)
	ds_read_b128 v[168:171], v198 offset:224
	ds_read_b128 v[172:175], v198 offset:192
	ds_read_b128 v[220:223], v198 offset:160
	ds_read_b128 v[224:227], v198 offset:128
	s_waitcnt lgkmcnt(3)
	v_pk_mul_f32 v[16:17], v[16:17], v[170:171]
	s_waitcnt lgkmcnt(2)
	v_pk_mul_f32 v[12:13], v[12:13], v[174:175]
	s_waitcnt lgkmcnt(1)
	v_pk_mul_f32 v[8:9], v[8:9], v[222:223]
	s_waitcnt lgkmcnt(0)
	v_pk_mul_f32 v[4:5], v[4:5], v[226:227]
	v_pk_mul_f32 v[14:15], v[14:15], v[168:169]
	v_pk_mul_f32 v[10:11], v[10:11], v[172:173]
	v_pk_mul_f32 v[6:7], v[6:7], v[220:221]
	v_pk_mul_f32 v[2:3], v[2:3], v[224:225]
	v_pk_mul_f32 v[64:65], v[64:65], v[170:171]
	v_pk_mul_f32 v[60:61], v[60:61], v[174:175]
	v_pk_mul_f32 v[56:57], v[56:57], v[222:223]
	v_pk_mul_f32 v[52:53], v[52:53], v[226:227]
	v_pk_mul_f32 v[62:63], v[62:63], v[168:169]
	v_pk_mul_f32 v[58:59], v[58:59], v[172:173]
	v_pk_mul_f32 v[54:55], v[54:55], v[220:221]
	v_pk_mul_f32 v[50:51], v[50:51], v[224:225]
	v_pk_mul_f32 v[48:49], v[48:49], v[170:171]
	v_pk_mul_f32 v[44:45], v[44:45], v[174:175]
	v_pk_mul_f32 v[40:41], v[40:41], v[222:223]
	v_pk_mul_f32 v[36:37], v[36:37], v[226:227]
	v_pk_mul_f32 v[46:47], v[46:47], v[168:169]
	v_pk_mul_f32 v[42:43], v[42:43], v[172:173]
	v_pk_mul_f32 v[38:39], v[38:39], v[220:221]
	v_pk_mul_f32 v[34:35], v[34:35], v[224:225]
	v_pk_mul_f32 v[32:33], v[32:33], v[170:171]
	v_pk_mul_f32 v[28:29], v[28:29], v[174:175]
	v_pk_mul_f32 v[24:25], v[24:25], v[222:223]
	v_pk_mul_f32 v[20:21], v[20:21], v[226:227]
	v_pk_mul_f32 v[30:31], v[30:31], v[168:169]
	v_pk_mul_f32 v[26:27], v[26:27], v[172:173]
	v_pk_mul_f32 v[22:23], v[22:23], v[220:221]
	v_pk_mul_f32 v[18:19], v[18:19], v[224:225]

.Lattn_k2:
	ds_write_b128 v203, v[154:157] offset:49152
	ds_write_b128 v204, v[158:161] offset:49152
	ds_read_b64_tr_b16 v[224:225], v197 offset:0
	ds_read_b64_tr_b16 v[226:227], v197 offset:0x800
	ds_read_b64_tr_b16 v[228:229], v197 offset:0x1000
	ds_read_b64_tr_b16 v[230:231], v197 offset:0x1800
	ds_read_b64_tr_b16 v[232:233], v197 offset:0x2000
	ds_read_b64_tr_b16 v[234:235], v197 offset:0x2800
	ds_read_b64_tr_b16 v[236:237], v197 offset:0x3000
	ds_read_b64_tr_b16 v[238:239], v197 offset:0x3800
	s_nop 0
	s_waitcnt lgkmcnt(6)
	v_mfma_f32_32x32x16_bf16 v[2:17], v[162:165], v[224:227], v[2:17]
	ds_read_b64_tr_b16 v[224:225], v197 offset:0x200
	ds_read_b64_tr_b16 v[226:227], v197 offset:0xa00
	s_waitcnt lgkmcnt(6)
	v_mfma_f32_32x32x16_bf16 v[2:17], v[166:169], v[228:231], v[2:17]
	ds_read_b64_tr_b16 v[228:229], v197 offset:0x1200
	ds_read_b64_tr_b16 v[230:231], v197 offset:0x1a00
	s_waitcnt lgkmcnt(6)
	v_mfma_f32_32x32x16_bf16 v[2:17], v[170:173], v[232:235], v[2:17]
	ds_read_b64_tr_b16 v[232:233], v197 offset:0x2200
	ds_read_b64_tr_b16 v[234:235], v197 offset:0x2a00
	ds_read_b64_tr_b16 v[240:241], v197 offset:0x3200
	ds_read_b64_tr_b16 v[242:243], v197 offset:0x3a00
	s_waitcnt lgkmcnt(8)
	v_mfma_f32_32x32x16_bf16 v[2:17], v[174:177], v[236:239], v[2:17]
	s_waitcnt lgkmcnt(6)
	v_mfma_f32_32x32x16_bf16 v[50:65], v[162:165], v[224:227], v[50:65]
	ds_read_b64_tr_b16 v[224:225], v197 offset:0x400
	ds_read_b64_tr_b16 v[226:227], v197 offset:0xc00
	s_waitcnt lgkmcnt(6)
	v_mfma_f32_32x32x16_bf16 v[50:65], v[166:169], v[228:231], v[50:65]
	ds_read_b64_tr_b16 v[228:229], v197 offset:0x1400
	ds_read_b64_tr_b16 v[230:231], v197 offset:0x1c00
	s_waitcnt lgkmcnt(6)
	v_mfma_f32_32x32x16_bf16 v[50:65], v[170:173], v[232:235], v[50:65]
	ds_read_b64_tr_b16 v[232:233], v197 offset:0x2400
	ds_read_b64_tr_b16 v[234:235], v197 offset:0x2c00
	ds_read_b64_tr_b16 v[236:237], v197 offset:0x3400
	ds_read_b64_tr_b16 v[238:239], v197 offset:0x3c00
	s_waitcnt lgkmcnt(8)
	v_mfma_f32_32x32x16_bf16 v[50:65], v[174:177], v[240:243], v[50:65]
	s_waitcnt lgkmcnt(6)
	v_mfma_f32_32x32x16_bf16 v[34:49], v[162:165], v[224:227], v[34:49]
	ds_read_b64_tr_b16 v[224:225], v197 offset:0x600
	ds_read_b64_tr_b16 v[226:227], v197 offset:0xe00
	s_waitcnt lgkmcnt(6)
	v_mfma_f32_32x32x16_bf16 v[34:49], v[166:169], v[228:231], v[34:49]
	ds_read_b64_tr_b16 v[228:229], v197 offset:0x1600
	ds_read_b64_tr_b16 v[230:231], v197 offset:0x1e00
	s_waitcnt lgkmcnt(6)
	v_mfma_f32_32x32x16_bf16 v[34:49], v[170:173], v[232:235], v[34:49]
	ds_read_b64_tr_b16 v[232:233], v197 offset:0x2600
	ds_read_b64_tr_b16 v[234:235], v197 offset:0x2e00
	ds_read_b64_tr_b16 v[240:241], v197 offset:0x3600
	ds_read_b64_tr_b16 v[242:243], v197 offset:0x3e00
	s_waitcnt lgkmcnt(8)
	v_mfma_f32_32x32x16_bf16 v[34:49], v[174:177], v[236:239], v[34:49]
	s_waitcnt lgkmcnt(6)
	v_mfma_f32_32x32x16_bf16 v[18:33], v[162:165], v[224:227], v[18:33]
	v_max_f32_e32 v223, v83, v83
	v_max_f32_e32 v236, v82, v82
	v_max_f32_e32 v223, v236, v223
	v_max3_f32 v223, v223, v84, v85
	v_max3_f32 v223, v223, v86, v87
	v_max3_f32 v162, v223, v88, v89
	v_max3_f32 v162, v162, v90, v91
	v_max3_f32 v162, v162, v92, v93
	s_waitcnt lgkmcnt(4)
	v_mfma_f32_32x32x16_bf16 v[18:33], v[166:169], v[228:231], v[18:33]
	v_max3_f32 v162, v162, v94, v95
	v_max3_f32 v162, v162, v96, v97
	v_max3_f32 v162, v162, v66, v67
	v_max3_f32 v162, v162, v68, v69
	v_max3_f32 v162, v162, v70, v71
	v_max3_f32 v162, v162, v72, v73
	v_max3_f32 v162, v162, v74, v75
	v_max3_f32 v162, v162, v76, v77
	s_waitcnt lgkmcnt(2)
	v_mfma_f32_32x32x16_bf16 v[18:33], v[170:173], v[232:235], v[18:33]
	v_max3_f32 v162, v162, v78, v79
	v_max3_f32 v162, v162, v80, v81
	v_mov_b32_e32 v163, v162
	s_nop 1
	v_permlane32_swap_b32_e32 v162, v163
	v_max_f32_e32 v163, v163, v163
	v_max_f32_e32 v162, v162, v162
	v_max_f32_e32 v162, v162, v163
	v_max_f32_e32 v163, v220, v220
	v_max_f32_e32 v163, v163, v162
	v_sub_f32_e32 v164, v162, v220
	s_waitcnt lgkmcnt(0)
	v_mfma_f32_32x32x16_bf16 v[18:33], v[174:177], v[240:243], v[18:33]
	v_sub_f32_e32 v162, v220, v163
	v_mul_f32_e32 v162, 0x3e0293ee, v162
	v_exp_f32_e32 v162, v162
	v_cmp_ge_f32_e32 vcc, s37, v164
	s_cmp_eq_u64 vcc, exec
	s_cselect_b64 s[6:7], -1, 0
	s_barrier
	s_waitcnt vmcnt(4)
	v_cndmask_b32_e64 v162, v162, 1.0, s[6:7]
	v_cmp_gt_f32_e32 vcc, 1.0, v162
	ds_write_b128 v201, v[146:149] offset:16384
	ds_write_b128 v202, v[150:153] offset:16384
	s_cbranch_vccz .LBB0_2073
	s_and_saveexec_b64 s[14:15], s[4:5]
	ds_write_b32 v196, v162 offset:128
	s_or_b64 exec, exec, s[14:15]
	s_waitcnt lgkmcnt(0)
	ds_read_b128 v[146:149], v198 offset:224
	ds_read_b128 v[150:153], v198 offset:192
	ds_read_b128 v[154:157], v198 offset:160
	ds_read_b128 v[158:161], v198 offset:128
	s_waitcnt lgkmcnt(3)
	v_pk_mul_f32 v[16:17], v[16:17], v[148:149]
	s_waitcnt lgkmcnt(2)
	v_pk_mul_f32 v[12:13], v[12:13], v[152:153]
	s_waitcnt lgkmcnt(1)
	v_pk_mul_f32 v[8:9], v[8:9], v[156:157]
	s_waitcnt lgkmcnt(0)
	v_pk_mul_f32 v[4:5], v[4:5], v[160:161]
	v_pk_mul_f32 v[14:15], v[14:15], v[146:147]
	v_pk_mul_f32 v[10:11], v[10:11], v[150:151]
	v_pk_mul_f32 v[6:7], v[6:7], v[154:155]
	v_pk_mul_f32 v[2:3], v[2:3], v[158:159]
	v_pk_mul_f32 v[64:65], v[64:65], v[148:149]
	v_pk_mul_f32 v[60:61], v[60:61], v[152:153]
	v_pk_mul_f32 v[56:57], v[56:57], v[156:157]
	v_pk_mul_f32 v[52:53], v[52:53], v[160:161]
	v_pk_mul_f32 v[62:63], v[62:63], v[146:147]
	v_pk_mul_f32 v[58:59], v[58:59], v[150:151]
	v_pk_mul_f32 v[54:55], v[54:55], v[154:155]
	v_pk_mul_f32 v[50:51], v[50:51], v[158:159]
	v_pk_mul_f32 v[48:49], v[48:49], v[148:149]
	v_pk_mul_f32 v[44:45], v[44:45], v[152:153]
	v_pk_mul_f32 v[40:41], v[40:41], v[156:157]
	v_pk_mul_f32 v[36:37], v[36:37], v[160:161]
	v_pk_mul_f32 v[46:47], v[46:47], v[146:147]
	v_pk_mul_f32 v[42:43], v[42:43], v[150:151]
	v_pk_mul_f32 v[38:39], v[38:39], v[154:155]
	v_pk_mul_f32 v[34:35], v[34:35], v[158:159]
	v_pk_mul_f32 v[32:33], v[32:33], v[148:149]
	v_pk_mul_f32 v[28:29], v[28:29], v[152:153]
	v_pk_mul_f32 v[24:25], v[24:25], v[156:157]
	v_pk_mul_f32 v[20:21], v[20:21], v[160:161]
	v_pk_mul_f32 v[30:31], v[30:31], v[146:147]
	v_pk_mul_f32 v[26:27], v[26:27], v[150:151]
	v_pk_mul_f32 v[22:23], v[22:23], v[154:155]
	v_pk_mul_f32 v[18:19], v[18:19], v[158:159]

.LBB0_2075:
	ds_read_b128 v[66:69], v205 offset:49152
	ds_read_b128 v[70:73], v205 offset:57344
	v_exp_f32_e32 v156, v156
	v_exp_f32_e32 v157, v157
	v_exp_f32_e32 v154, v154
	s_waitcnt lgkmcnt(1)
	v_mfma_f32_32x32x16_bf16 v[82:97], v[66:69], v[126:129], 0
	v_exp_f32_e32 v155, v155
	v_exp_f32_e32 v150, v150
	s_waitcnt lgkmcnt(0)
	v_mfma_f32_32x32x16_bf16 v[66:81], v[70:73], v[126:129], 0
	ds_read_b128 v[126:129], v206 offset:49152
	ds_read_b128 v[130:133], v206 offset:57344
	ds_read_b128 v[134:137], v207 offset:49152
	ds_read_b128 v[138:141], v207 offset:57344
	s_waitcnt lgkmcnt(3)
	v_mfma_f32_32x32x16_bf16 v[82:97], v[126:129], v[122:125], v[82:97]
	ds_read_b128 v[126:129], v208 offset:49152
	ds_read_b128 v[142:145], v208 offset:57344
	ds_read_b128 v[224:227], v209 offset:49152
	ds_read_b128 v[228:231], v209 offset:57344
	ds_read_b128 v[232:235], v210 offset:49152
	ds_read_b128 v[236:239], v210 offset:57344
	ds_read_b128 v[240:243], v211 offset:49152
	ds_read_b128 v[244:247], v211 offset:57344
	s_waitcnt lgkmcnt(10)
	v_mfma_f32_32x32x16_bf16 v[66:81], v[130:133], v[122:125], v[66:81]
	ds_read_b128 v[122:125], v212 offset:49152
	ds_read_b128 v[130:133], v212 offset:57344
	s_waitcnt lgkmcnt(11)
	v_mfma_f32_32x32x16_bf16 v[82:97], v[134:137], v[118:121], v[82:97]
	v_exp_f32_e32 v134, v151
	v_exp_f32_e32 v135, v148
	v_exp_f32_e32 v136, v149
	v_exp_f32_e32 v137, v146
	v_exp_f32_e32 v146, v147
	v_exp_f32_e32 v147, v160
	v_exp_f32_e32 v148, v161
	s_waitcnt lgkmcnt(10)
	v_mfma_f32_32x32x16_bf16 v[66:81], v[138:141], v[118:121], v[66:81]
	v_add_f32_e32 v118, 0, v177
	v_add_f32_e32 v118, v223, v118
	v_add_f32_e32 v118, v163, v118
	v_add_f32_e32 v118, v220, v118
	v_add_f32_e32 v118, v164, v118
	v_add_f32_e32 v118, v176, v118
	v_add_f32_e32 v118, v165, v118
	s_waitcnt lgkmcnt(9)
	v_mfma_f32_32x32x16_bf16 v[82:97], v[126:129], v[114:117], v[82:97]
	v_add_f32_e32 v118, v175, v118
	v_add_f32_e32 v118, v172, v118
	v_add_f32_e32 v118, v174, v118
	v_exp_f32_e32 v120, v158
	v_exp_f32_e32 v121, v159
	v_exp_f32_e32 v138, v152
	v_exp_f32_e32 v139, v153
	s_waitcnt lgkmcnt(8)
	v_mfma_f32_32x32x16_bf16 v[66:81], v[142:145], v[114:117], v[66:81]
	v_add_f32_e32 v114, v171, v118
	v_add_f32_e32 v114, v173, v114
	v_add_f32_e32 v114, v168, v114
	v_add_f32_e32 v114, v170, v114
	v_add_f32_e32 v114, v167, v114
	v_add_f32_e32 v114, v169, v114
	v_add_f32_e32 v114, v156, v114
	s_waitcnt lgkmcnt(7)
	v_mfma_f32_32x32x16_bf16 v[82:97], v[224:227], v[110:113], v[82:97]
	v_add_f32_e32 v114, v157, v114
	v_add_f32_e32 v114, v154, v114
	v_add_f32_e32 v114, v155, v114
	v_add_f32_e32 v114, v150, v114
	v_add_f32_e32 v114, v134, v114
	v_add_f32_e32 v114, v135, v114
	v_add_f32_e32 v114, v136, v114
	s_waitcnt lgkmcnt(6)
	v_mfma_f32_32x32x16_bf16 v[66:81], v[228:231], v[110:113], v[66:81]
	v_add_f32_e32 v110, v137, v114
	v_add_f32_e32 v110, v146, v110
	v_add_f32_e32 v110, v147, v110
	v_add_f32_e32 v110, v148, v110
	v_add_f32_e32 v110, v120, v110
	v_add_f32_e32 v110, v121, v110
	v_add_f32_e32 v110, v138, v110
	s_waitcnt lgkmcnt(5)
	v_mfma_f32_32x32x16_bf16 v[82:97], v[232:235], v[106:109], v[82:97]
	v_add_f32_e32 v110, v139, v110
	v_mov_b32_e32 v111, v110
	s_nop 1
	v_permlane32_swap_b32_e32 v110, v111
	v_cvt_pk_bf16_f32 v112, v177, v223
	v_cvt_pk_bf16_f32 v113, v163, v220
	v_cvt_pk_bf16_f32 v114, v164, v176
	s_waitcnt lgkmcnt(4)
	v_mfma_f32_32x32x16_bf16 v[66:81], v[236:239], v[106:109], v[66:81]
	v_cvt_pk_bf16_f32 v115, v165, v175
	v_cvt_pk_bf16_f32 v106, v172, v174
	v_cvt_pk_bf16_f32 v107, v171, v173
	v_cvt_pk_bf16_f32 v108, v168, v170
	v_cvt_pk_bf16_f32 v109, v167, v169
	v_cvt_pk_bf16_f32 v116, v156, v157
	v_cvt_pk_bf16_f32 v117, v154, v155
	s_waitcnt lgkmcnt(3)
	v_mfma_f32_32x32x16_bf16 v[82:97], v[240:243], v[102:105], v[82:97]
	v_cvt_pk_bf16_f32 v118, v150, v134
	v_cvt_pk_bf16_f32 v119, v135, v136
	v_permlane32_swap_b32_e32 v112, v114
	v_permlane32_swap_b32_e32 v113, v115
	v_permlane32_swap_b32_e32 v106, v108
	s_waitcnt lgkmcnt(2)
	v_mfma_f32_32x32x16_bf16 v[66:81], v[244:247], v[102:105], v[66:81]
	v_cvt_pk_bf16_f32 v102, v137, v146
	v_cvt_pk_bf16_f32 v103, v147, v148
	v_cvt_pk_bf16_f32 v104, v120, v121
	v_cvt_pk_bf16_f32 v105, v138, v139
	v_permlane32_swap_b32_e32 v107, v109
	v_permlane32_swap_b32_e32 v116, v118
	s_waitcnt lgkmcnt(1)
	v_mfma_f32_32x32x16_bf16 v[82:97], v[122:125], v[98:101], v[82:97]
	v_permlane32_swap_b32_e32 v117, v119
	v_permlane32_swap_b32_e32 v102, v104
	v_permlane32_swap_b32_e32 v103, v105
	s_waitcnt lgkmcnt(0)
	v_mfma_f32_32x32x16_bf16 v[66:81], v[130:133], v[98:101], v[66:81]
	ds_read_b64_tr_b16 v[98:99], v1 offset:0
	ds_read_b64_tr_b16 v[100:101], v1 offset:0x800
	ds_read_b64_tr_b16 v[120:121], v1 offset:0x1000
	ds_read_b64_tr_b16 v[122:123], v1 offset:0x1800
	ds_read_b64_tr_b16 v[124:125], v1 offset:0x2000
	ds_read_b64_tr_b16 v[126:127], v1 offset:0x2800
	ds_read_b64_tr_b16 v[128:129], v1 offset:0x3000
	ds_read_b64_tr_b16 v[130:131], v1 offset:0x3800
	s_nop 0
	s_waitcnt lgkmcnt(6)
	v_mfma_f32_32x32x16_bf16 v[2:17], v[112:115], v[98:101], v[2:17]
	ds_read_b64_tr_b16 v[98:99], v1 offset:0x200
	ds_read_b64_tr_b16 v[100:101], v1 offset:0xa00
	s_waitcnt lgkmcnt(6)
	v_mfma_f32_32x32x16_bf16 v[2:17], v[106:109], v[120:123], v[2:17]
	ds_read_b64_tr_b16 v[120:121], v1 offset:0x1200
	ds_read_b64_tr_b16 v[122:123], v1 offset:0x1a00
	s_waitcnt lgkmcnt(6)
	v_mfma_f32_32x32x16_bf16 v[2:17], v[116:119], v[124:127], v[2:17]
	ds_read_b64_tr_b16 v[124:125], v1 offset:0x2200
	ds_read_b64_tr_b16 v[126:127], v1 offset:0x2a00
	ds_read_b64_tr_b16 v[132:133], v1 offset:0x3200
	ds_read_b64_tr_b16 v[134:135], v1 offset:0x3a00
	s_waitcnt lgkmcnt(8)
	v_mfma_f32_32x32x16_bf16 v[2:17], v[102:105], v[128:131], v[2:17]
	s_waitcnt lgkmcnt(6)
	v_mfma_f32_32x32x16_bf16 v[50:65], v[112:115], v[98:101], v[50:65]
	ds_read_b64_tr_b16 v[98:99], v1 offset:0x400
	ds_read_b64_tr_b16 v[100:101], v1 offset:0xc00
	s_waitcnt lgkmcnt(6)
	v_mfma_f32_32x32x16_bf16 v[50:65], v[106:109], v[120:123], v[50:65]
	ds_read_b64_tr_b16 v[120:121], v1 offset:0x1400
	ds_read_b64_tr_b16 v[122:123], v1 offset:0x1c00
	s_waitcnt lgkmcnt(6)
	v_mfma_f32_32x32x16_bf16 v[50:65], v[116:119], v[124:127], v[50:65]
	ds_read_b64_tr_b16 v[124:125], v1 offset:0x2400
	ds_read_b64_tr_b16 v[126:127], v1 offset:0x2c00
	ds_read_b64_tr_b16 v[128:129], v1 offset:0x3400
	ds_read_b64_tr_b16 v[130:131], v1 offset:0x3c00
	s_waitcnt lgkmcnt(8)
	v_mfma_f32_32x32x16_bf16 v[50:65], v[102:105], v[132:135], v[50:65]
	s_waitcnt lgkmcnt(6)
	v_mfma_f32_32x32x16_bf16 v[34:49], v[112:115], v[98:101], v[34:49]
	ds_read_b64_tr_b16 v[98:99], v1 offset:0x600
	ds_read_b64_tr_b16 v[100:101], v1 offset:0xe00
	s_waitcnt lgkmcnt(6)
	v_mfma_f32_32x32x16_bf16 v[34:49], v[106:109], v[120:123], v[34:49]
	ds_read_b64_tr_b16 v[120:121], v1 offset:0x1600
	ds_read_b64_tr_b16 v[122:123], v1 offset:0x1e00
	s_waitcnt lgkmcnt(6)
	v_mfma_f32_32x32x16_bf16 v[34:49], v[116:119], v[124:127], v[34:49]
	ds_read_b64_tr_b16 v[124:125], v1 offset:0x2600
	ds_read_b64_tr_b16 v[126:127], v1 offset:0x2e00
	ds_read_b64_tr_b16 v[132:133], v1 offset:0x3600
	ds_read_b64_tr_b16 v[134:135], v1 offset:0x3e00
	s_waitcnt lgkmcnt(8)
	v_mfma_f32_32x32x16_bf16 v[34:49], v[102:105], v[128:131], v[34:49]
	s_waitcnt lgkmcnt(6)
	v_mfma_f32_32x32x16_bf16 v[18:33], v[112:115], v[98:101], v[18:33]
	v_max_f32_e32 v128, v83, v83
	v_max_f32_e32 v129, v82, v82
	v_max_f32_e32 v128, v129, v128
	v_max3_f32 v128, v128, v84, v85
	v_max3_f32 v128, v128, v86, v87
	v_max3_f32 v98, v128, v88, v89
	v_max3_f32 v98, v98, v90, v91
	v_max3_f32 v98, v98, v92, v93
	s_waitcnt lgkmcnt(4)
	v_mfma_f32_32x32x16_bf16 v[18:33], v[106:109], v[120:123], v[18:33]
	v_max3_f32 v98, v98, v94, v95
	v_max3_f32 v98, v98, v96, v97
	v_max3_f32 v98, v98, v66, v67
	v_max3_f32 v98, v98, v68, v69
	v_max3_f32 v98, v98, v70, v71
	v_max3_f32 v98, v98, v72, v73
	v_max3_f32 v98, v98, v74, v75
	v_max3_f32 v98, v98, v76, v77
	s_waitcnt lgkmcnt(2)
	v_mfma_f32_32x32x16_bf16 v[18:33], v[116:119], v[124:127], v[18:33]
	v_max3_f32 v98, v98, v78, v79
	v_max3_f32 v98, v98, v80, v81
	v_mov_b32_e32 v99, v98
	s_nop 1
	v_permlane32_swap_b32_e32 v98, v99
	v_max_f32_e32 v99, v99, v99
	v_max_f32_e32 v98, v98, v98
	v_max_f32_e32 v98, v98, v99
	v_max_f32_e32 v99, v166, v166
	v_max_f32_e32 v99, v99, v98
	v_sub_f32_e32 v100, v98, v166
	s_waitcnt lgkmcnt(0)
	v_mfma_f32_32x32x16_bf16 v[18:33], v[102:105], v[132:135], v[18:33]
	v_sub_f32_e32 v98, v166, v99
	v_mul_f32_e32 v98, 0x3e0293ee, v98
	v_exp_f32_e32 v98, v98
	v_cmp_ge_f32_e32 vcc, s37, v100
	s_cmp_eq_u64 vcc, exec
	s_cselect_b64 s[6:7], -1, 0
	v_cndmask_b32_e64 v98, v98, 1.0, s[6:7]
	v_cmp_gt_f32_e32 vcc, 1.0, v98
	s_barrier
	s_cbranch_vccz .LBB0_2079
	s_and_saveexec_b64 s[10:11], s[4:5]
	ds_write_b32 v196, v98 offset:128
	s_or_b64 exec, exec, s[10:11]
	s_waitcnt lgkmcnt(0)
	ds_read_b128 v[100:103], v198 offset:224
	ds_read_b128 v[104:107], v198 offset:192
	ds_read_b128 v[112:115], v198 offset:160
	ds_read_b128 v[116:119], v198 offset:128
	s_waitcnt lgkmcnt(3)
	v_pk_mul_f32 v[16:17], v[16:17], v[102:103]
	s_waitcnt lgkmcnt(2)
	v_pk_mul_f32 v[12:13], v[12:13], v[106:107]
	s_waitcnt lgkmcnt(1)
	v_pk_mul_f32 v[8:9], v[8:9], v[114:115]
	s_waitcnt lgkmcnt(0)
	v_pk_mul_f32 v[4:5], v[4:5], v[118:119]
	v_pk_mul_f32 v[14:15], v[14:15], v[100:101]
	v_pk_mul_f32 v[10:11], v[10:11], v[104:105]
	v_pk_mul_f32 v[6:7], v[6:7], v[112:113]
	v_pk_mul_f32 v[2:3], v[2:3], v[116:117]
	v_pk_mul_f32 v[64:65], v[64:65], v[102:103]
	v_pk_mul_f32 v[60:61], v[60:61], v[106:107]
	v_pk_mul_f32 v[56:57], v[56:57], v[114:115]
	v_pk_mul_f32 v[52:53], v[52:53], v[118:119]
	v_pk_mul_f32 v[62:63], v[62:63], v[100:101]
	v_pk_mul_f32 v[58:59], v[58:59], v[104:105]
	v_pk_mul_f32 v[54:55], v[54:55], v[112:113]
	v_pk_mul_f32 v[50:51], v[50:51], v[116:117]
	v_pk_mul_f32 v[48:49], v[48:49], v[102:103]
	v_pk_mul_f32 v[44:45], v[44:45], v[106:107]
	v_pk_mul_f32 v[40:41], v[40:41], v[114:115]
	v_pk_mul_f32 v[36:37], v[36:37], v[118:119]
	v_pk_mul_f32 v[46:47], v[46:47], v[100:101]
	v_pk_mul_f32 v[42:43], v[42:43], v[104:105]
	v_pk_mul_f32 v[38:39], v[38:39], v[112:113]
	v_pk_mul_f32 v[34:35], v[34:35], v[116:117]
	v_pk_mul_f32 v[32:33], v[32:33], v[102:103]
	v_pk_mul_f32 v[28:29], v[28:29], v[106:107]
	v_pk_mul_f32 v[24:25], v[24:25], v[114:115]
	v_pk_mul_f32 v[20:21], v[20:21], v[118:119]
	v_pk_mul_f32 v[30:31], v[30:31], v[100:101]
	v_pk_mul_f32 v[26:27], v[26:27], v[104:105]
	v_pk_mul_f32 v[22:23], v[22:23], v[112:113]
	v_pk_mul_f32 v[18:19], v[18:19], v[116:117]
.LBB0_2079:
	v_cndmask_b32_e64 v99, v99, v166, s[6:7]
	v_mul_f32_e32 v99, 0xbe0293ee, v99
	v_fmamk_f32 v82, v82, 0x3e0293ee, v99
	v_fmamk_f32 v83, v83, 0x3e0293ee, v99
	v_fmamk_f32 v100, v84, 0x3e0293ee, v99
	v_exp_f32_e32 v84, v82
	v_fmamk_f32 v101, v86, 0x3e0293ee, v99
	v_exp_f32_e32 v86, v83
	v_fmamk_f32 v85, v85, 0x3e0293ee, v99
	v_exp_f32_e32 v82, v100
	v_fmamk_f32 v66, v66, 0x3e0293ee, v99
	v_exp_f32_e32 v85, v85
	v_fmamk_f32 v102, v87, 0x3e0293ee, v99
	v_fmamk_f32 v113, v96, 0x3e0293ee, v99
	v_fmamk_f32 v96, v77, 0x3e0293ee, v99
	v_exp_f32_e32 v77, v101
	v_exp_f32_e32 v100, v66
	v_add_f32_e32 v66, 0, v84
	v_fmamk_f32 v103, v88, 0x3e0293ee, v99
	v_exp_f32_e32 v83, v102
	v_add_f32_e32 v66, v86, v66
	v_fmamk_f32 v104, v89, 0x3e0293ee, v99
	v_fmamk_f32 v112, v95, 0x3e0293ee, v99
	v_fmamk_f32 v95, v76, 0x3e0293ee, v99
	v_exp_f32_e32 v76, v103
	v_add_f32_e32 v66, v82, v66
	v_fmamk_f32 v105, v90, 0x3e0293ee, v99
	v_fmamk_f32 v114, v97, 0x3e0293ee, v99
	v_fmamk_f32 v97, v78, 0x3e0293ee, v99
	v_exp_f32_e32 v78, v104
	v_add_f32_e32 v66, v85, v66
	v_fmamk_f32 v106, v91, 0x3e0293ee, v99
	v_fmamk_f32 v107, v92, 0x3e0293ee, v99
	v_fmamk_f32 v92, v73, 0x3e0293ee, v99
	v_exp_f32_e32 v73, v105
	v_add_f32_e32 v66, v77, v66
	v_fmamk_f32 v109, v94, 0x3e0293ee, v99
	v_fmamk_f32 v94, v75, 0x3e0293ee, v99
	v_exp_f32_e32 v75, v106
	v_add_f32_e32 v66, v83, v66
	v_fmamk_f32 v108, v93, 0x3e0293ee, v99
	v_fmamk_f32 v90, v71, 0x3e0293ee, v99
	v_exp_f32_e32 v71, v107
	v_add_f32_e32 v66, v76, v66
	v_fmamk_f32 v93, v74, 0x3e0293ee, v99
	v_exp_f32_e32 v74, v108
	v_add_f32_e32 v66, v78, v66
	v_fmamk_f32 v88, v69, 0x3e0293ee, v99
	v_exp_f32_e32 v69, v109
	v_add_f32_e32 v66, v73, v66
	v_fmamk_f32 v91, v72, 0x3e0293ee, v99
	v_exp_f32_e32 v72, v112
	v_add_f32_e32 v66, v75, v66
	v_fmamk_f32 v87, v68, 0x3e0293ee, v99
	v_exp_f32_e32 v68, v113
	v_add_f32_e32 v66, v71, v66
	v_fmamk_f32 v89, v70, 0x3e0293ee, v99
	v_exp_f32_e32 v70, v114
	v_add_f32_e32 v66, v74, v66
	v_fmamk_f32 v67, v67, 0x3e0293ee, v99
	v_add_f32_e32 v66, v69, v66
	v_exp_f32_e32 v101, v67
	v_add_f32_e32 v66, v72, v66
	v_exp_f32_e32 v87, v87
	v_add_f32_e32 v66, v68, v66
	v_exp_f32_e32 v88, v88
	v_add_f32_e32 v66, v70, v66
	v_exp_f32_e32 v89, v89
	v_add_f32_e32 v66, v100, v66
	v_exp_f32_e32 v90, v90
	v_add_f32_e32 v66, v101, v66
	v_exp_f32_e32 v91, v91
	v_add_f32_e32 v66, v87, v66
	v_exp_f32_e32 v92, v92
	v_add_f32_e32 v66, v88, v66
	v_exp_f32_e32 v93, v93
	v_add_f32_e32 v66, v89, v66
	v_exp_f32_e32 v94, v94
	v_add_f32_e32 v66, v90, v66
	v_exp_f32_e32 v95, v95
	v_add_f32_e32 v66, v91, v66
	v_exp_f32_e32 v96, v96
	v_add_f32_e32 v66, v92, v66
	v_fmamk_f32 v79, v79, 0x3e0293ee, v99
	v_exp_f32_e32 v97, v97
	v_add_f32_e32 v66, v93, v66
	v_fmamk_f32 v80, v80, 0x3e0293ee, v99
	v_exp_f32_e32 v102, v79
	v_add_f32_e32 v66, v94, v66
	v_fmac_f32_e32 v99, 0x3e0293ee, v81
	v_exp_f32_e32 v103, v80
	v_add_f32_e32 v66, v95, v66
	v_exp_f32_e32 v99, v99
	v_add_f32_e32 v66, v96, v66
	v_add_f32_e32 v66, v97, v66
	v_add_f32_e32 v66, v102, v66
	v_add_f32_e32 v66, v103, v66
	v_add_f32_e32 v66, v99, v66
	v_mov_b32_e32 v67, v66
	s_nop 1
	v_permlane32_swap_b32_e32 v66, v67
	v_cvt_pk_bf16_f32 v80, v84, v86
	v_cvt_pk_bf16_f32 v81, v82, v85
	v_cvt_pk_bf16_f32 v82, v77, v83
	v_cvt_pk_bf16_f32 v83, v76, v78
	v_cvt_pk_bf16_f32 v76, v73, v75
	v_cvt_pk_bf16_f32 v77, v71, v74
	v_cvt_pk_bf16_f32 v78, v69, v72
	v_cvt_pk_bf16_f32 v79, v68, v70
	v_cvt_pk_bf16_f32 v68, v100, v101
	v_cvt_pk_bf16_f32 v69, v87, v88
	v_cvt_pk_bf16_f32 v70, v89, v90
	v_cvt_pk_bf16_f32 v71, v91, v92
	v_cvt_pk_bf16_f32 v72, v93, v94
	v_cvt_pk_bf16_f32 v73, v95, v96
	v_cvt_pk_bf16_f32 v74, v97, v102
	v_cvt_pk_bf16_f32 v75, v103, v99
	s_nop 0
	v_permlane32_swap_b32_e32 v80, v82
	v_permlane32_swap_b32_e32 v81, v83
	v_permlane32_swap_b32_e32 v76, v78
	v_permlane32_swap_b32_e32 v77, v79
	v_permlane32_swap_b32_e32 v68, v70
	v_permlane32_swap_b32_e32 v69, v71
	v_permlane32_swap_b32_e32 v72, v74
	v_permlane32_swap_b32_e32 v73, v75
	ds_read_b64_tr_b16 v[84:85], v197 offset:0
	ds_read_b64_tr_b16 v[86:87], v197 offset:0x800
	ds_read_b64_tr_b16 v[88:89], v197 offset:0x1000
	ds_read_b64_tr_b16 v[90:91], v197 offset:0x1800
	ds_read_b64_tr_b16 v[92:93], v197 offset:0x2000
	ds_read_b64_tr_b16 v[94:95], v197 offset:0x2800
	ds_read_b64_tr_b16 v[100:101], v197 offset:0x3000
	ds_read_b64_tr_b16 v[102:103], v197 offset:0x3800
	s_nop 0
	s_waitcnt lgkmcnt(6)
	v_mfma_f32_32x32x16_bf16 v[2:17], v[80:83], v[84:87], v[2:17]
	ds_read_b64_tr_b16 v[84:85], v197 offset:0x200
	ds_read_b64_tr_b16 v[86:87], v197 offset:0xa00
	s_waitcnt lgkmcnt(6)
	v_mfma_f32_32x32x16_bf16 v[2:17], v[76:79], v[88:91], v[2:17]
	ds_read_b64_tr_b16 v[88:89], v197 offset:0x1200
	ds_read_b64_tr_b16 v[90:91], v197 offset:0x1a00
	s_waitcnt lgkmcnt(6)
	v_mfma_f32_32x32x16_bf16 v[2:17], v[68:71], v[92:95], v[2:17]
	ds_read_b64_tr_b16 v[92:93], v197 offset:0x2200
	ds_read_b64_tr_b16 v[94:95], v197 offset:0x2a00
	ds_read_b64_tr_b16 v[104:105], v197 offset:0x3200
	ds_read_b64_tr_b16 v[106:107], v197 offset:0x3a00
	s_waitcnt lgkmcnt(8)
	v_mfma_f32_32x32x16_bf16 v[2:17], v[72:75], v[100:103], v[2:17]
	s_waitcnt lgkmcnt(6)
	v_mfma_f32_32x32x16_bf16 v[50:65], v[80:83], v[84:87], v[50:65]
	ds_read_b64_tr_b16 v[84:85], v197 offset:0x400
	ds_read_b64_tr_b16 v[86:87], v197 offset:0xc00
	s_waitcnt lgkmcnt(6)
	v_mfma_f32_32x32x16_bf16 v[50:65], v[76:79], v[88:91], v[50:65]
	ds_read_b64_tr_b16 v[88:89], v197 offset:0x1400
	ds_read_b64_tr_b16 v[90:91], v197 offset:0x1c00
	s_waitcnt lgkmcnt(6)
	v_mfma_f32_32x32x16_bf16 v[50:65], v[68:71], v[92:95], v[50:65]
	ds_read_b64_tr_b16 v[92:93], v197 offset:0x2400
	ds_read_b64_tr_b16 v[94:95], v197 offset:0x2c00
	ds_read_b64_tr_b16 v[100:101], v197 offset:0x3400
	ds_read_b64_tr_b16 v[102:103], v197 offset:0x3c00
	s_waitcnt lgkmcnt(8)
	v_mfma_f32_32x32x16_bf16 v[50:65], v[72:75], v[104:107], v[50:65]
	s_waitcnt lgkmcnt(6)
	v_mfma_f32_32x32x16_bf16 v[34:49], v[80:83], v[84:87], v[34:49]
	ds_read_b64_tr_b16 v[84:85], v197 offset:0x600
	ds_read_b64_tr_b16 v[86:87], v197 offset:0xe00
	s_waitcnt lgkmcnt(6)
	v_mfma_f32_32x32x16_bf16 v[34:49], v[76:79], v[88:91], v[34:49]
	ds_read_b64_tr_b16 v[88:89], v197 offset:0x1600
	ds_read_b64_tr_b16 v[90:91], v197 offset:0x1e00
	s_waitcnt lgkmcnt(6)
	v_mfma_f32_32x32x16_bf16 v[34:49], v[68:71], v[92:95], v[34:49]
	ds_read_b64_tr_b16 v[92:93], v197 offset:0x2600
	ds_read_b64_tr_b16 v[94:95], v197 offset:0x2e00
	ds_read_b64_tr_b16 v[104:105], v197 offset:0x3600
	ds_read_b64_tr_b16 v[106:107], v197 offset:0x3e00
	s_waitcnt lgkmcnt(8)
	v_mfma_f32_32x32x16_bf16 v[34:49], v[72:75], v[100:103], v[34:49]
	s_waitcnt lgkmcnt(6)
	v_mfma_f32_32x32x16_bf16 v[18:33], v[80:83], v[84:87], v[18:33]
	s_waitcnt lgkmcnt(4)
	v_mfma_f32_32x32x16_bf16 v[18:33], v[76:79], v[88:91], v[18:33]
	s_waitcnt lgkmcnt(2)
	v_mfma_f32_32x32x16_bf16 v[18:33], v[68:71], v[92:95], v[18:33]
	s_waitcnt lgkmcnt(0)
	v_mfma_f32_32x32x16_bf16 v[18:33], v[72:75], v[104:107], v[18:33]
	s_and_saveexec_b64 s[6:7], s[4:5]
	s_cbranch_execz .LBB0_2054
	v_add_f32_e32 v68, v110, v111
	v_fmac_f32_e32 v68, v191, v162
	v_add_f32_e32 v66, v66, v67
	v_fmac_f32_e32 v66, v68, v98
	ds_write_b32 v196, v66
	s_branch .LBB0_2054
.LBB0_2081:
	s_cmp_lt_i32 s61, 30
	s_cbranch_scc1 .LBB0_2131
	s_setprio 0
	s_waitcnt vmcnt(0)
	v_cmp_eq_u32_e32 vcc, 0, v0
	s_barrier
	s_and_saveexec_b64 s[4:5], vcc
	s_cbranch_execz .LBB0_2130
	v_readlane_b32 s3, v255, 10
	s_waitcnt vmcnt(0) expcnt(0) lgkmcnt(0)
	s_nop 0
	v_mov_b32_e32 v1, s3
	ds_read_b32 v3, v1
	ds_read_b32 v1, v1 offset:4
	s_waitcnt lgkmcnt(1)
	v_cmp_ne_u32_e32 vcc, 0, v3
	s_cbranch_vccnz .LBB0_2098
	v_readlane_b32 s6, v255, 0
	v_readlane_b32 s7, v255, 1
	s_load_dwordx2 s[10:11], s[6:7], 0x4
	s_add_u32 s6, s52, 0x4200
	s_addc_u32 s7, s53, 0
	s_add_u32 s8, s52, 0x4400
	s_addc_u32 s9, s53, 0
	s_waitcnt lgkmcnt(0)
	s_mul_i32 s3, s10, s56
	s_add_u32 s10, s52, 0x4500
	s_mul_i32 s3, s3, s11
	s_addc_u32 s11, s53, 0
	s_add_u32 s12, s52, 0x4600
	s_addc_u32 s13, s53, 0
	s_add_u32 s14, s52, 0x4700
	s_addc_u32 s15, s53, 0
	s_add_u32 s16, s52, 0x4800
	s_addc_u32 s17, s53, 0
	s_add_u32 s18, s52, 0x4900
	s_addc_u32 s19, s53, 0
	s_add_u32 s20, s52, 0x4a00
	s_addc_u32 s21, s53, 0
	s_add_u32 s22, s52, 0x4b00
	s_addc_u32 s23, s53, 0
	s_add_u32 s24, s52, 0x4c00
	s_addc_u32 s25, s53, 0
	s_add_u32 s26, s52, 0x4d00
	s_addc_u32 s27, s53, 0
	s_add_u32 s28, s52, 0x4e00
	s_addc_u32 s29, s53, 0
	s_add_u32 s30, s52, 0x4f00
	s_addc_u32 s31, s53, 0
	s_add_u32 s34, s52, 0x5000
	s_addc_u32 s35, s53, 0
	s_add_u32 s36, s52, 0x5100
	s_addc_u32 s37, s53, 0
	s_add_u32 s38, s52, 0x5200
	s_addc_u32 s39, s53, 0
	s_add_u32 s42, s52, 0x5300
	s_addc_u32 s43, s53, 0
	s_mov_b32 s41, 1
	v_mov_b32_e32 v17, 0
	s_branch .LBB0_2086
